# best4 + norm_unit also touches the V slice (16 throw-away loads/thread) to warm caches for attention
# speedup vs baseline: 1.0140x; 1.0140x over previous
; __device__ __forceinline__ float bf_lo(unsigned w) { return __uint_as_float(w << 16); }
; __device__ __forceinline__ float bf_hi(unsigned w) { return __uint_as_float(w & 0xffff0000u); }
; __device__ __forceinline__ void norm_unit(const Ctx& c, int l, int tile) {
;     const int tid = c.tid, tok = tile * 128 + (tid >> 2), part = tid & 3, b = tile >> 5;
;     const bf16_t* Q = (const bf16_t*)(c.ws + WS_Z + 1 * ZARR); const bf16_t* K = (const bf16_t*)(c.ws + WS_Z + 2 * ZARR);
;     unsigned* nrm = (unsigned*)(c.ws + WS_NORM) + (size_t)l * 128;
;     float res[4];
; #pragma unroll
;     for (int a = 0; a < 2; ++a)
; #pragma unroll
;         for (int hh = 0; hh < 2; ++hh) { const u32x4* p = (const u32x4*)((a == 0 ? Q : K) + (size_t)tok * 512 + (2 * part + hh) * 64);
;             float s0 = 0.f, s1 = 0.f;
; #pragma unroll
;             for (int j = 0; j < 8; ++j) { const u32x4 w = p[j];
;                 s0 += bf_lo(w.x) * bf_lo(w.x) + bf_hi(w.x) * bf_hi(w.x) + bf_lo(w.y) * bf_lo(w.y) + bf_hi(w.y) * bf_hi(w.y);
;                 s1 += bf_lo(w.z) * bf_lo(w.z) + bf_hi(w.z) * bf_hi(w.z) + bf_lo(w.w) * bf_lo(w.w) + bf_hi(w.w) * bf_hi(w.w); }
;             res[a * 2 + hh] = (s0 + s1) * 1.0001f + 1e-30f; }
.LBB0_314:
	v_readlane_b32 s12, v253, 0
	v_readlane_b32 s13, v253, 1
	s_load_dwordx4 s[20:23], s[12:13], 0xa8
	v_ashrrev_i32_e32 v17, 31, v16
	s_waitcnt lgkmcnt(0)
	v_lshlrev_b64 v[0:1], 10, v[16:17]
	s_mov_b64 s[12:13], 0x4000000
	s_mov_b64 s[42:43], 0x6000000
	s_waitcnt lgkmcnt(0)
	v_lshl_add_u64 v[12:13], s[22:23], 0, v[0:1]
	v_lshl_add_u64 v[14:15], v[12:13], 0, s[12:13]
	v_lshl_add_u64 v[20:21], v[14:15], 0, v[96:97]
	global_load_dwordx4 v[0:3], v[20:21], off offset:48
	global_load_dwordx4 v[4:7], v[20:21], off offset:32
	global_load_dwordx4 v[8:11], v[20:21], off offset:16
	global_load_dwordx4 v[28:31], v[20:21], off
	v_lshl_add_u64 v[160:161], v[20:21], 0, s[12:13]
	global_load_dwordx4 v[156:159], v[160:161], off
	global_load_dwordx4 v[156:159], v[160:161], off offset:16
	global_load_dwordx4 v[156:159], v[160:161], off offset:32
	global_load_dwordx4 v[156:159], v[160:161], off offset:48
	global_load_dwordx4 v[156:159], v[160:161], off offset:64
	global_load_dwordx4 v[156:159], v[160:161], off offset:80
	global_load_dwordx4 v[156:159], v[160:161], off offset:96
	global_load_dwordx4 v[156:159], v[160:161], off offset:112
	global_load_dwordx4 v[156:159], v[160:161], off offset:128
	global_load_dwordx4 v[156:159], v[160:161], off offset:144
	global_load_dwordx4 v[156:159], v[160:161], off offset:160
	global_load_dwordx4 v[156:159], v[160:161], off offset:176
	global_load_dwordx4 v[156:159], v[160:161], off offset:192
	global_load_dwordx4 v[156:159], v[160:161], off offset:208
	global_load_dwordx4 v[156:159], v[160:161], off offset:224
	global_load_dwordx4 v[156:159], v[160:161], off offset:240
	v_lshl_add_u64 v[12:13], v[12:13], 0, s[42:43]
	s_waitcnt vmcnt(0)
	v_and_b32_e32 v19, 0xffff0000, v28
	v_lshlrev_b32_e32 v17, 16, v28
	v_mul_f32_e32 v19, v19, v19
	v_fmac_f32_e32 v19, v17, v17
	v_lshlrev_b32_e32 v17, 16, v29
	v_fmac_f32_e32 v19, v17, v17
	v_and_b32_e32 v17, 0xffff0000, v29
	v_and_b32_e32 v28, 0xffff0000, v30
	v_fmac_f32_e32 v19, v17, v17
	v_lshlrev_b32_e32 v17, 16, v30
	v_mul_f32_e32 v28, v28, v28
	v_fmac_f32_e32 v28, v17, v17
	v_lshlrev_b32_e32 v17, 16, v31
	v_fmac_f32_e32 v28, v17, v17
	v_and_b32_e32 v17, 0xffff0000, v31
	v_fmac_f32_e32 v28, v17, v17
	v_lshlrev_b32_e32 v17, 16, v8
	v_and_b32_e32 v8, 0xffff0000, v8
	v_mul_f32_e32 v8, v8, v8
	v_fmac_f32_e32 v8, v17, v17
	v_lshlrev_b32_e32 v17, 16, v9
	v_fmac_f32_e32 v8, v17, v17
	v_and_b32_e32 v9, 0xffff0000, v9
	v_fmac_f32_e32 v8, v9, v9
	v_lshlrev_b32_e32 v9, 16, v10
	v_and_b32_e32 v10, 0xffff0000, v10
	v_mul_f32_e32 v10, v10, v10
	v_fmac_f32_e32 v10, v9, v9
	v_lshlrev_b32_e32 v9, 16, v11
	v_fmac_f32_e32 v10, v9, v9
	v_and_b32_e32 v9, 0xffff0000, v11
	v_fmac_f32_e32 v10, v9, v9
	v_add_f32_e32 v9, v28, v10
	v_lshlrev_b32_e32 v10, 16, v4
	v_and_b32_e32 v4, 0xffff0000, v4
	v_mul_f32_e32 v4, v4, v4
	v_fmac_f32_e32 v4, v10, v10
	v_lshlrev_b32_e32 v10, 16, v5
	v_fmac_f32_e32 v4, v10, v10
	v_and_b32_e32 v5, 0xffff0000, v5
	v_fmac_f32_e32 v4, v5, v5
	v_lshlrev_b32_e32 v5, 16, v6
	v_and_b32_e32 v6, 0xffff0000, v6
	v_mul_f32_e32 v6, v6, v6
	v_fmac_f32_e32 v6, v5, v5
	v_lshlrev_b32_e32 v5, 16, v7
	v_fmac_f32_e32 v6, v5, v5
	v_and_b32_e32 v5, 0xffff0000, v7
	v_fmac_f32_e32 v6, v5, v5
	v_add_f32_e32 v5, v9, v6
	v_lshlrev_b32_e32 v6, 16, v0
	v_and_b32_e32 v0, 0xffff0000, v0
	v_mul_f32_e32 v0, v0, v0
	v_fmac_f32_e32 v0, v6, v6
	v_lshlrev_b32_e32 v6, 16, v1
	v_add_f32_e32 v8, v19, v8
	v_fmac_f32_e32 v0, v6, v6
	v_and_b32_e32 v1, 0xffff0000, v1
	v_add_f32_e32 v4, v8, v4
	v_fmac_f32_e32 v0, v1, v1
	v_and_b32_e32 v1, 0xffff0000, v2
	v_add_f32_e32 v17, v4, v0
	v_lshlrev_b32_e32 v0, 16, v2
	v_mul_f32_e32 v1, v1, v1
	v_fmac_f32_e32 v1, v0, v0
	v_lshlrev_b32_e32 v0, 16, v3
	v_fmac_f32_e32 v1, v0, v0
	v_and_b32_e32 v0, 0xffff0000, v3
	v_fmac_f32_e32 v1, v0, v0
	v_add_f32_e32 v19, v5, v1
	global_load_dwordx4 v[0:3], v[20:21], off offset:112
	global_load_dwordx4 v[4:7], v[20:21], off offset:96
	global_load_dwordx4 v[8:11], v[20:21], off offset:80
	global_load_dwordx4 v[28:31], v[20:21], off offset:64
	s_waitcnt vmcnt(0)
	v_and_b32_e32 v21, 0xffff0000, v28
	v_lshlrev_b32_e32 v20, 16, v28
	v_mul_f32_e32 v21, v21, v21
	v_fmac_f32_e32 v21, v20, v20
	v_lshlrev_b32_e32 v20, 16, v29
	v_fmac_f32_e32 v21, v20, v20
	v_and_b32_e32 v20, 0xffff0000, v29
	v_fmac_f32_e32 v21, v20, v20
	v_add_f32_e32 v17, v17, v21
	v_and_b32_e32 v21, 0xffff0000, v30
	v_lshlrev_b32_e32 v20, 16, v30
	v_mul_f32_e32 v21, v21, v21
	v_fmac_f32_e32 v21, v20, v20
	v_lshlrev_b32_e32 v20, 16, v31
	v_fmac_f32_e32 v21, v20, v20
	v_and_b32_e32 v20, 0xffff0000, v31
	v_fmac_f32_e32 v21, v20, v20
	v_lshlrev_b32_e32 v20, 16, v8
	v_and_b32_e32 v8, 0xffff0000, v8
	v_mul_f32_e32 v8, v8, v8
	v_fmac_f32_e32 v8, v20, v20
	v_lshlrev_b32_e32 v20, 16, v9
	v_fmac_f32_e32 v8, v20, v20
	v_and_b32_e32 v9, 0xffff0000, v9
	v_fmac_f32_e32 v8, v9, v9
	v_lshlrev_b32_e32 v9, 16, v10
	v_and_b32_e32 v10, 0xffff0000, v10
	v_mul_f32_e32 v10, v10, v10
	v_fmac_f32_e32 v10, v9, v9
	v_lshlrev_b32_e32 v9, 16, v11
	v_fmac_f32_e32 v10, v9, v9
	v_and_b32_e32 v9, 0xffff0000, v11
	v_add_f32_e32 v19, v19, v21
	v_fmac_f32_e32 v10, v9, v9
	v_add_f32_e32 v9, v19, v10
	v_lshlrev_b32_e32 v10, 16, v4
	v_and_b32_e32 v4, 0xffff0000, v4
	v_mul_f32_e32 v4, v4, v4
	v_fmac_f32_e32 v4, v10, v10
	v_lshlrev_b32_e32 v10, 16, v5
	v_fmac_f32_e32 v4, v10, v10
	v_and_b32_e32 v5, 0xffff0000, v5
	v_fmac_f32_e32 v4, v5, v5
	v_lshlrev_b32_e32 v5, 16, v6
	v_and_b32_e32 v6, 0xffff0000, v6
	v_mul_f32_e32 v6, v6, v6
	v_fmac_f32_e32 v6, v5, v5
	v_lshlrev_b32_e32 v5, 16, v7
	v_fmac_f32_e32 v6, v5, v5
	v_and_b32_e32 v5, 0xffff0000, v7
	v_fmac_f32_e32 v6, v5, v5
	v_add_f32_e32 v5, v9, v6
	v_lshlrev_b32_e32 v6, 16, v0
	v_and_b32_e32 v0, 0xffff0000, v0
	v_mul_f32_e32 v0, v0, v0
	v_fmac_f32_e32 v0, v6, v6
	v_lshlrev_b32_e32 v6, 16, v1
	v_fmac_f32_e32 v0, v6, v6
	v_and_b32_e32 v1, 0xffff0000, v1
	v_fmac_f32_e32 v0, v1, v1
	v_lshlrev_b32_e32 v1, 16, v2
	v_and_b32_e32 v2, 0xffff0000, v2
	v_mul_f32_e32 v2, v2, v2
	v_fmac_f32_e32 v2, v1, v1
	v_lshlrev_b32_e32 v1, 16, v3
	v_add_f32_e32 v8, v17, v8
	v_fmac_f32_e32 v2, v1, v1
	v_and_b32_e32 v1, 0xffff0000, v3
	v_add_f32_e32 v4, v8, v4
	v_fmac_f32_e32 v2, v1, v1
	v_add_f32_e32 v0, v4, v0
	v_add_f32_e32 v1, v5, v2
	v_mov_b32_e32 v19, v97
	v_add_f32_e32 v0, v0, v1
	v_lshl_add_u64 v[14:15], v[14:15], 0, v[18:19]
	v_fmamk_f32 v17, v0, 0x3f800347, v217
	global_load_dwordx4 v[0:3], v[14:15], off offset:48
	global_load_dwordx4 v[4:7], v[14:15], off offset:32
	global_load_dwordx4 v[8:11], v[14:15], off offset:16
	global_load_dwordx4 v[28:31], v[14:15], off
	s_waitcnt vmcnt(0)
; __device__ __forceinline__ float bf_lo(unsigned w) { return __uint_as_float(w << 16); }
; __device__ __forceinline__ float bf_hi(unsigned w) { return __uint_as_float(w & 0xffff0000u); }
; __device__ __forceinline__ void norm_unit(const Ctx& c, int l, int tile) {
;     ...
;         for (int hh = 0; hh < 2; ++hh) { const u32x4* p = (const u32x4*)((a == 0 ? Q : K) + (size_t)tok * 512 + (2 * part + hh) * 64);
;             float s0 = 0.f, s1 = 0.f;
; #pragma unroll
;             for (int j = 0; j < 8; ++j) { const u32x4 w = p[j];
;                 s0 += bf_lo(w.x) * bf_lo(w.x) + bf_hi(w.x) * bf_hi(w.x) + bf_lo(w.y) * bf_lo(w.y) + bf_hi(w.y) * bf_hi(w.y);
;                 s1 += bf_lo(w.z) * bf_lo(w.z) + bf_hi(w.z) * bf_hi(w.z) + bf_lo(w.w) * bf_lo(w.w) + bf_hi(w.w) * bf_hi(w.w); }
;             res[a * 2 + hh] = (s0 + s1) * 1.0001f + 1e-30f; }
	v_and_b32_e32 v21, 0xffff0000, v28
	v_lshlrev_b32_e32 v20, 16, v28
	v_mul_f32_e32 v21, v21, v21
	v_fmac_f32_e32 v21, v20, v20
	v_lshlrev_b32_e32 v20, 16, v29
	v_fmac_f32_e32 v21, v20, v20
	v_and_b32_e32 v20, 0xffff0000, v29
	v_and_b32_e32 v28, 0xffff0000, v30
	v_fmac_f32_e32 v21, v20, v20
	v_lshlrev_b32_e32 v20, 16, v30
	v_mul_f32_e32 v28, v28, v28
	v_fmac_f32_e32 v28, v20, v20
	v_lshlrev_b32_e32 v20, 16, v31
	v_fmac_f32_e32 v28, v20, v20
	v_and_b32_e32 v20, 0xffff0000, v31
	v_fmac_f32_e32 v28, v20, v20
	v_lshlrev_b32_e32 v20, 16, v8
	v_and_b32_e32 v8, 0xffff0000, v8
	v_mul_f32_e32 v8, v8, v8
	v_fmac_f32_e32 v8, v20, v20
	v_lshlrev_b32_e32 v20, 16, v9
	v_fmac_f32_e32 v8, v20, v20
	v_and_b32_e32 v9, 0xffff0000, v9
	v_fmac_f32_e32 v8, v9, v9
	v_lshlrev_b32_e32 v9, 16, v10
	v_and_b32_e32 v10, 0xffff0000, v10
	v_mul_f32_e32 v10, v10, v10
	v_fmac_f32_e32 v10, v9, v9
	v_lshlrev_b32_e32 v9, 16, v11
	v_fmac_f32_e32 v10, v9, v9
	v_and_b32_e32 v9, 0xffff0000, v11
	v_fmac_f32_e32 v10, v9, v9
	v_add_f32_e32 v9, v28, v10
	v_lshlrev_b32_e32 v10, 16, v4
	v_and_b32_e32 v4, 0xffff0000, v4
	v_mul_f32_e32 v4, v4, v4
	v_fmac_f32_e32 v4, v10, v10
	v_lshlrev_b32_e32 v10, 16, v5
	v_fmac_f32_e32 v4, v10, v10
	v_and_b32_e32 v5, 0xffff0000, v5
	v_fmac_f32_e32 v4, v5, v5
	v_lshlrev_b32_e32 v5, 16, v6
	v_and_b32_e32 v6, 0xffff0000, v6
	v_mul_f32_e32 v6, v6, v6
	v_fmac_f32_e32 v6, v5, v5
	v_lshlrev_b32_e32 v5, 16, v7
	v_fmac_f32_e32 v6, v5, v5
	v_and_b32_e32 v5, 0xffff0000, v7
	v_fmac_f32_e32 v6, v5, v5
	v_add_f32_e32 v5, v9, v6
	v_lshlrev_b32_e32 v6, 16, v0
	v_and_b32_e32 v0, 0xffff0000, v0
	v_mul_f32_e32 v0, v0, v0
	v_fmac_f32_e32 v0, v6, v6
	v_lshlrev_b32_e32 v6, 16, v1
	v_add_f32_e32 v8, v21, v8
	v_fmac_f32_e32 v0, v6, v6
	v_and_b32_e32 v1, 0xffff0000, v1
	v_add_f32_e32 v4, v8, v4
	v_fmac_f32_e32 v0, v1, v1
	v_and_b32_e32 v1, 0xffff0000, v2
	v_add_f32_e32 v20, v4, v0
	v_lshlrev_b32_e32 v0, 16, v2
	v_mul_f32_e32 v1, v1, v1
	v_fmac_f32_e32 v1, v0, v0
	v_lshlrev_b32_e32 v0, 16, v3
	v_fmac_f32_e32 v1, v0, v0
	v_and_b32_e32 v0, 0xffff0000, v3
	v_fmac_f32_e32 v1, v0, v0
	v_add_f32_e32 v21, v5, v1
	global_load_dwordx4 v[0:3], v[14:15], off offset:112
	global_load_dwordx4 v[4:7], v[14:15], off offset:96
	global_load_dwordx4 v[8:11], v[14:15], off offset:80
	global_load_dwordx4 v[28:31], v[14:15], off offset:64
	s_waitcnt vmcnt(0)
	v_and_b32_e32 v15, 0xffff0000, v28
	v_lshlrev_b32_e32 v14, 16, v28
	v_mul_f32_e32 v15, v15, v15
	v_fmac_f32_e32 v15, v14, v14
	v_lshlrev_b32_e32 v14, 16, v29
	v_fmac_f32_e32 v15, v14, v14
	v_and_b32_e32 v14, 0xffff0000, v29
	v_fmac_f32_e32 v15, v14, v14
	v_add_f32_e32 v14, v20, v15
	v_and_b32_e32 v20, 0xffff0000, v30
	v_lshlrev_b32_e32 v15, 16, v30
	v_mul_f32_e32 v20, v20, v20
	v_fmac_f32_e32 v20, v15, v15
	v_lshlrev_b32_e32 v15, 16, v31
	v_fmac_f32_e32 v20, v15, v15
	v_and_b32_e32 v15, 0xffff0000, v31
	v_fmac_f32_e32 v20, v15, v15
	v_add_f32_e32 v15, v21, v20
	v_lshlrev_b32_e32 v20, 16, v8
	v_and_b32_e32 v8, 0xffff0000, v8
	v_mul_f32_e32 v8, v8, v8
	v_fmac_f32_e32 v8, v20, v20
	v_lshlrev_b32_e32 v20, 16, v9
	v_fmac_f32_e32 v8, v20, v20
	v_and_b32_e32 v9, 0xffff0000, v9
	v_fmac_f32_e32 v8, v9, v9
	v_lshlrev_b32_e32 v9, 16, v10
	v_and_b32_e32 v10, 0xffff0000, v10
	v_mul_f32_e32 v10, v10, v10
	v_fmac_f32_e32 v10, v9, v9
	v_lshlrev_b32_e32 v9, 16, v11
	v_fmac_f32_e32 v10, v9, v9
	v_and_b32_e32 v9, 0xffff0000, v11
	v_fmac_f32_e32 v10, v9, v9
	v_add_f32_e32 v9, v15, v10
	v_lshlrev_b32_e32 v10, 16, v4
	v_and_b32_e32 v4, 0xffff0000, v4
	v_mul_f32_e32 v4, v4, v4
	v_fmac_f32_e32 v4, v10, v10
	v_lshlrev_b32_e32 v10, 16, v5
	v_fmac_f32_e32 v4, v10, v10
	v_and_b32_e32 v5, 0xffff0000, v5
	v_fmac_f32_e32 v4, v5, v5
	v_lshlrev_b32_e32 v5, 16, v6
	v_and_b32_e32 v6, 0xffff0000, v6
	v_mul_f32_e32 v6, v6, v6
	v_fmac_f32_e32 v6, v5, v5
	v_lshlrev_b32_e32 v5, 16, v7
	v_fmac_f32_e32 v6, v5, v5
	v_and_b32_e32 v5, 0xffff0000, v7
	v_fmac_f32_e32 v6, v5, v5
	v_add_f32_e32 v5, v9, v6
	v_lshlrev_b32_e32 v6, 16, v0
	v_and_b32_e32 v0, 0xffff0000, v0
	v_mul_f32_e32 v0, v0, v0
	v_fmac_f32_e32 v0, v6, v6
	v_lshlrev_b32_e32 v6, 16, v1
	v_fmac_f32_e32 v0, v6, v6
	v_and_b32_e32 v1, 0xffff0000, v1
	v_fmac_f32_e32 v0, v1, v1
	v_lshlrev_b32_e32 v1, 16, v2
	v_and_b32_e32 v2, 0xffff0000, v2
	v_mul_f32_e32 v2, v2, v2
	v_fmac_f32_e32 v2, v1, v1
	v_lshlrev_b32_e32 v1, 16, v3
	v_add_f32_e32 v8, v14, v8
	v_fmac_f32_e32 v2, v1, v1
	v_and_b32_e32 v1, 0xffff0000, v3
	v_add_f32_e32 v4, v8, v4
	v_fmac_f32_e32 v2, v1, v1
	v_add_f32_e32 v0, v4, v0
	v_add_f32_e32 v1, v5, v2
	v_add_f32_e32 v0, v0, v1
	v_lshl_add_u64 v[14:15], v[12:13], 0, v[96:97]
	v_fmamk_f32 v20, v0, 0x3f800347, v217
	global_load_dwordx4 v[0:3], v[14:15], off offset:48
	global_load_dwordx4 v[4:7], v[14:15], off offset:32
	global_load_dwordx4 v[8:11], v[14:15], off offset:16
	global_load_dwordx4 v[28:31], v[14:15], off
	v_lshl_add_u64 v[12:13], v[12:13], 0, v[18:19]
	s_waitcnt vmcnt(0)
; __device__ __forceinline__ float bf_lo(unsigned w) { return __uint_as_float(w << 16); }
; __device__ __forceinline__ float bf_hi(unsigned w) { return __uint_as_float(w & 0xffff0000u); }
; __device__ __forceinline__ void norm_unit(const Ctx& c, int l, int tile) {
;     ...
;         for (int hh = 0; hh < 2; ++hh) { const u32x4* p = (const u32x4*)((a == 0 ? Q : K) + (size_t)tok * 512 + (2 * part + hh) * 64);
;             float s0 = 0.f, s1 = 0.f;
; #pragma unroll
;             for (int j = 0; j < 8; ++j) { const u32x4 w = p[j];
;                 s0 += bf_lo(w.x) * bf_lo(w.x) + bf_hi(w.x) * bf_hi(w.x) + bf_lo(w.y) * bf_lo(w.y) + bf_hi(w.y) * bf_hi(w.y);
;                 s1 += bf_lo(w.z) * bf_lo(w.z) + bf_hi(w.z) * bf_hi(w.z) + bf_lo(w.w) * bf_lo(w.w) + bf_hi(w.w) * bf_hi(w.w); }
;             res[a * 2 + hh] = (s0 + s1) * 1.0001f + 1e-30f; }
	v_lshlrev_b32_e32 v21, 16, v28
	v_and_b32_e32 v28, 0xffff0000, v28
	v_mul_f32_e32 v28, v28, v28
	v_fmac_f32_e32 v28, v21, v21
	v_lshlrev_b32_e32 v21, 16, v29
	v_fmac_f32_e32 v28, v21, v21
	v_and_b32_e32 v21, 0xffff0000, v29
	v_and_b32_e32 v29, 0xffff0000, v30
	v_fmac_f32_e32 v28, v21, v21
	v_lshlrev_b32_e32 v21, 16, v30
	v_mul_f32_e32 v29, v29, v29
	v_fmac_f32_e32 v29, v21, v21
	v_lshlrev_b32_e32 v21, 16, v31
	v_fmac_f32_e32 v29, v21, v21
	v_and_b32_e32 v21, 0xffff0000, v31
	v_fmac_f32_e32 v29, v21, v21
	v_lshlrev_b32_e32 v21, 16, v8
	v_and_b32_e32 v8, 0xffff0000, v8
	v_mul_f32_e32 v8, v8, v8
	v_fmac_f32_e32 v8, v21, v21
	v_lshlrev_b32_e32 v21, 16, v9
	v_fmac_f32_e32 v8, v21, v21
	v_and_b32_e32 v9, 0xffff0000, v9
	v_fmac_f32_e32 v8, v9, v9
	v_lshlrev_b32_e32 v9, 16, v10
	v_and_b32_e32 v10, 0xffff0000, v10
	v_mul_f32_e32 v10, v10, v10
	v_fmac_f32_e32 v10, v9, v9
	v_lshlrev_b32_e32 v9, 16, v11
	v_fmac_f32_e32 v10, v9, v9
	v_and_b32_e32 v9, 0xffff0000, v11
	v_fmac_f32_e32 v10, v9, v9
	v_add_f32_e32 v9, v29, v10
	v_lshlrev_b32_e32 v10, 16, v4
	v_and_b32_e32 v4, 0xffff0000, v4
	v_mul_f32_e32 v4, v4, v4
	v_fmac_f32_e32 v4, v10, v10
	v_lshlrev_b32_e32 v10, 16, v5
	v_fmac_f32_e32 v4, v10, v10
	v_and_b32_e32 v5, 0xffff0000, v5
	v_fmac_f32_e32 v4, v5, v5
	v_lshlrev_b32_e32 v5, 16, v6
	v_and_b32_e32 v6, 0xffff0000, v6
	v_mul_f32_e32 v6, v6, v6
	v_fmac_f32_e32 v6, v5, v5
	v_lshlrev_b32_e32 v5, 16, v7
	v_fmac_f32_e32 v6, v5, v5
	v_and_b32_e32 v5, 0xffff0000, v7
	v_fmac_f32_e32 v6, v5, v5
	v_add_f32_e32 v5, v9, v6
	v_lshlrev_b32_e32 v6, 16, v0
	v_and_b32_e32 v0, 0xffff0000, v0
	v_mul_f32_e32 v0, v0, v0
	v_fmac_f32_e32 v0, v6, v6
	v_lshlrev_b32_e32 v6, 16, v1
	v_add_f32_e32 v8, v28, v8
	v_fmac_f32_e32 v0, v6, v6
	v_and_b32_e32 v1, 0xffff0000, v1
	v_add_f32_e32 v4, v8, v4
	v_fmac_f32_e32 v0, v1, v1
	v_and_b32_e32 v1, 0xffff0000, v2
	v_add_f32_e32 v21, v4, v0
	v_lshlrev_b32_e32 v0, 16, v2
	v_mul_f32_e32 v1, v1, v1
	v_fmac_f32_e32 v1, v0, v0
	v_lshlrev_b32_e32 v0, 16, v3
	v_fmac_f32_e32 v1, v0, v0
	v_and_b32_e32 v0, 0xffff0000, v3
	v_fmac_f32_e32 v1, v0, v0
	v_add_f32_e32 v28, v5, v1
	global_load_dwordx4 v[0:3], v[14:15], off offset:112
	global_load_dwordx4 v[4:7], v[14:15], off offset:96
	global_load_dwordx4 v[8:11], v[14:15], off offset:80
	global_load_dwordx4 v[30:33], v[14:15], off offset:64
	s_waitcnt vmcnt(0)
	v_and_b32_e32 v15, 0xffff0000, v30
	v_lshlrev_b32_e32 v14, 16, v30
	v_mul_f32_e32 v15, v15, v15
	v_fmac_f32_e32 v15, v14, v14
	v_lshlrev_b32_e32 v14, 16, v31
	v_fmac_f32_e32 v15, v14, v14
	v_and_b32_e32 v14, 0xffff0000, v31
	v_fmac_f32_e32 v15, v14, v14
	v_add_f32_e32 v14, v21, v15
	v_and_b32_e32 v21, 0xffff0000, v32
	v_lshlrev_b32_e32 v15, 16, v32
	v_mul_f32_e32 v21, v21, v21
	v_fmac_f32_e32 v21, v15, v15
	v_lshlrev_b32_e32 v15, 16, v33
	v_fmac_f32_e32 v21, v15, v15
	v_and_b32_e32 v15, 0xffff0000, v33
	v_fmac_f32_e32 v21, v15, v15
	v_add_f32_e32 v15, v28, v21
	v_lshlrev_b32_e32 v21, 16, v8
	v_and_b32_e32 v8, 0xffff0000, v8
	v_mul_f32_e32 v8, v8, v8
	v_fmac_f32_e32 v8, v21, v21
	v_lshlrev_b32_e32 v21, 16, v9
	v_fmac_f32_e32 v8, v21, v21
	v_and_b32_e32 v9, 0xffff0000, v9
	v_fmac_f32_e32 v8, v9, v9
	v_lshlrev_b32_e32 v9, 16, v10
	v_and_b32_e32 v10, 0xffff0000, v10
	v_mul_f32_e32 v10, v10, v10
	v_fmac_f32_e32 v10, v9, v9
	v_lshlrev_b32_e32 v9, 16, v11
	v_fmac_f32_e32 v10, v9, v9
	v_and_b32_e32 v9, 0xffff0000, v11
	v_fmac_f32_e32 v10, v9, v9
	v_add_f32_e32 v9, v15, v10
	v_lshlrev_b32_e32 v10, 16, v4
	v_and_b32_e32 v4, 0xffff0000, v4
	v_mul_f32_e32 v4, v4, v4
	v_fmac_f32_e32 v4, v10, v10
	v_lshlrev_b32_e32 v10, 16, v5
	v_fmac_f32_e32 v4, v10, v10
	v_and_b32_e32 v5, 0xffff0000, v5
	v_fmac_f32_e32 v4, v5, v5
	v_lshlrev_b32_e32 v5, 16, v6
	v_and_b32_e32 v6, 0xffff0000, v6
	v_mul_f32_e32 v6, v6, v6
	v_fmac_f32_e32 v6, v5, v5
	v_lshlrev_b32_e32 v5, 16, v7
	v_fmac_f32_e32 v6, v5, v5
	v_and_b32_e32 v5, 0xffff0000, v7
	v_fmac_f32_e32 v6, v5, v5
	v_add_f32_e32 v5, v9, v6
	v_lshlrev_b32_e32 v6, 16, v0
	v_and_b32_e32 v0, 0xffff0000, v0
	v_mul_f32_e32 v0, v0, v0
	v_fmac_f32_e32 v0, v6, v6
	v_lshlrev_b32_e32 v6, 16, v1
	v_fmac_f32_e32 v0, v6, v6
	v_and_b32_e32 v1, 0xffff0000, v1
	v_fmac_f32_e32 v0, v1, v1
	v_lshlrev_b32_e32 v1, 16, v2
	v_and_b32_e32 v2, 0xffff0000, v2
	v_mul_f32_e32 v2, v2, v2
	v_fmac_f32_e32 v2, v1, v1
	v_lshlrev_b32_e32 v1, 16, v3
	v_add_f32_e32 v8, v14, v8
	v_fmac_f32_e32 v2, v1, v1
	v_and_b32_e32 v1, 0xffff0000, v3
	v_add_f32_e32 v4, v8, v4
	v_fmac_f32_e32 v2, v1, v1
	v_add_f32_e32 v0, v4, v0
	v_add_f32_e32 v1, v5, v2
	v_add_f32_e32 v0, v0, v1
	v_fmamk_f32 v21, v0, 0x3f800347, v217
	global_load_dwordx4 v[0:3], v[12:13], off offset:48
	global_load_dwordx4 v[4:7], v[12:13], off offset:32
	global_load_dwordx4 v[8:11], v[12:13], off offset:16
	global_load_dwordx4 v[28:31], v[12:13], off
	s_waitcnt vmcnt(0)
; __device__ __forceinline__ float bf_lo(unsigned w) { return __uint_as_float(w << 16); }
; __device__ __forceinline__ float bf_hi(unsigned w) { return __uint_as_float(w & 0xffff0000u); }
; __device__ __forceinline__ void norm_unit(const Ctx& c, int l, int tile) {
;     ...
;             for (int j = 0; j < 8; ++j) { const u32x4 w = p[j];
;                 s0 += bf_lo(w.x) * bf_lo(w.x) + bf_hi(w.x) * bf_hi(w.x) + bf_lo(w.y) * bf_lo(w.y) + bf_hi(w.y) * bf_hi(w.y);
;                 s1 += bf_lo(w.z) * bf_lo(w.z) + bf_hi(w.z) * bf_hi(w.z) + bf_lo(w.w) * bf_lo(w.w) + bf_hi(w.w) * bf_hi(w.w); }
;             res[a * 2 + hh] = (s0 + s1) * 1.0001f + 1e-30f; }
; #pragma unroll
;     for (int i = 0; i < 4; ++i) { float v = res[i];
; #pragma unroll
;         for (int o = 4; o < 64; o <<= 1) v = fmaxf(v, __shfl_xor(v, o));
;         res[i] = v; }
;     if (c.lane < 4) {
; #pragma unroll
;         for (int a = 0; a < 2; ++a)
; #pragma unroll
;             for (int hh = 0; hh < 2; ++hh) atomicMax(nrm + (size_t)(b * 8 + 2 * part + hh) * 2 + a, __float_as_uint(res[a * 2 + hh]));
;     }
	v_and_b32_e32 v15, 0xffff0000, v28
	v_lshlrev_b32_e32 v14, 16, v28
	v_mul_f32_e32 v15, v15, v15
	v_fmac_f32_e32 v15, v14, v14
	v_lshlrev_b32_e32 v14, 16, v29
	v_fmac_f32_e32 v15, v14, v14
	v_and_b32_e32 v14, 0xffff0000, v29
	v_and_b32_e32 v19, 0xffff0000, v30
	v_fmac_f32_e32 v15, v14, v14
	v_lshlrev_b32_e32 v14, 16, v30
	v_mul_f32_e32 v19, v19, v19
	v_fmac_f32_e32 v19, v14, v14
	v_lshlrev_b32_e32 v14, 16, v31
	v_fmac_f32_e32 v19, v14, v14
	v_and_b32_e32 v14, 0xffff0000, v31
	v_fmac_f32_e32 v19, v14, v14
	v_lshlrev_b32_e32 v14, 16, v8
	v_and_b32_e32 v8, 0xffff0000, v8
	v_mul_f32_e32 v8, v8, v8
	v_fmac_f32_e32 v8, v14, v14
	v_lshlrev_b32_e32 v14, 16, v9
	v_fmac_f32_e32 v8, v14, v14
	v_and_b32_e32 v9, 0xffff0000, v9
	v_fmac_f32_e32 v8, v9, v9
	v_lshlrev_b32_e32 v9, 16, v10
	v_and_b32_e32 v10, 0xffff0000, v10
	v_mul_f32_e32 v10, v10, v10
	v_fmac_f32_e32 v10, v9, v9
	v_lshlrev_b32_e32 v9, 16, v11
	v_fmac_f32_e32 v10, v9, v9
	v_and_b32_e32 v9, 0xffff0000, v11
	v_fmac_f32_e32 v10, v9, v9
	v_add_f32_e32 v9, v19, v10
	v_lshlrev_b32_e32 v10, 16, v4
	v_and_b32_e32 v4, 0xffff0000, v4
	v_mul_f32_e32 v4, v4, v4
	v_fmac_f32_e32 v4, v10, v10
	v_lshlrev_b32_e32 v10, 16, v5
	v_fmac_f32_e32 v4, v10, v10
	v_and_b32_e32 v5, 0xffff0000, v5
	v_fmac_f32_e32 v4, v5, v5
	v_lshlrev_b32_e32 v5, 16, v6
	v_and_b32_e32 v6, 0xffff0000, v6
	v_mul_f32_e32 v6, v6, v6
	v_fmac_f32_e32 v6, v5, v5
	v_lshlrev_b32_e32 v5, 16, v7
	v_fmac_f32_e32 v6, v5, v5
	v_and_b32_e32 v5, 0xffff0000, v7
	v_fmac_f32_e32 v6, v5, v5
	v_add_f32_e32 v5, v9, v6
	v_lshlrev_b32_e32 v6, 16, v0
	v_and_b32_e32 v0, 0xffff0000, v0
	v_mul_f32_e32 v0, v0, v0
	v_fmac_f32_e32 v0, v6, v6
	v_lshlrev_b32_e32 v6, 16, v1
	v_add_f32_e32 v8, v15, v8
	v_fmac_f32_e32 v0, v6, v6
	v_and_b32_e32 v1, 0xffff0000, v1
	v_add_f32_e32 v4, v8, v4
	v_fmac_f32_e32 v0, v1, v1
	v_and_b32_e32 v1, 0xffff0000, v2
	v_add_f32_e32 v28, v4, v0
	v_lshlrev_b32_e32 v0, 16, v2
	v_mul_f32_e32 v1, v1, v1
	v_fmac_f32_e32 v1, v0, v0
	v_lshlrev_b32_e32 v0, 16, v3
	v_fmac_f32_e32 v1, v0, v0
	v_and_b32_e32 v0, 0xffff0000, v3
	v_fmac_f32_e32 v1, v0, v0
	v_add_f32_e32 v19, v5, v1
	global_load_dwordx4 v[0:3], v[12:13], off offset:112
	global_load_dwordx4 v[4:7], v[12:13], off offset:96
	global_load_dwordx4 v[8:11], v[12:13], off offset:80
	s_nop 0
	global_load_dwordx4 v[12:15], v[12:13], off offset:64
	s_waitcnt vmcnt(0)
	v_lshlrev_b32_e32 v29, 16, v12
	v_and_b32_e32 v12, 0xffff0000, v12
	v_mul_f32_e32 v12, v12, v12
	v_fmac_f32_e32 v12, v29, v29
	v_lshlrev_b32_e32 v29, 16, v13
	v_fmac_f32_e32 v12, v29, v29
	v_and_b32_e32 v13, 0xffff0000, v13
	v_fmac_f32_e32 v12, v13, v13
	v_lshlrev_b32_e32 v13, 16, v14
	v_and_b32_e32 v14, 0xffff0000, v14
	v_mul_f32_e32 v14, v14, v14
	v_fmac_f32_e32 v14, v13, v13
	v_lshlrev_b32_e32 v13, 16, v15
	v_fmac_f32_e32 v14, v13, v13
	v_and_b32_e32 v13, 0xffff0000, v15
	v_fmac_f32_e32 v14, v13, v13
	v_add_f32_e32 v13, v19, v14
	v_lshlrev_b32_e32 v14, 16, v8
	v_and_b32_e32 v8, 0xffff0000, v8
	v_mul_f32_e32 v8, v8, v8
	v_fmac_f32_e32 v8, v14, v14
	v_lshlrev_b32_e32 v14, 16, v9
	v_fmac_f32_e32 v8, v14, v14
	v_and_b32_e32 v9, 0xffff0000, v9
	v_fmac_f32_e32 v8, v9, v9
	v_lshlrev_b32_e32 v9, 16, v10
	v_and_b32_e32 v10, 0xffff0000, v10
	v_mul_f32_e32 v10, v10, v10
	v_fmac_f32_e32 v10, v9, v9
	v_lshlrev_b32_e32 v9, 16, v11
	v_fmac_f32_e32 v10, v9, v9
	v_and_b32_e32 v9, 0xffff0000, v11
	v_fmac_f32_e32 v10, v9, v9
	v_add_f32_e32 v9, v13, v10
	v_lshlrev_b32_e32 v10, 16, v4
	v_and_b32_e32 v4, 0xffff0000, v4
	v_mul_f32_e32 v4, v4, v4
	v_fmac_f32_e32 v4, v10, v10
	v_lshlrev_b32_e32 v10, 16, v5
	v_fmac_f32_e32 v4, v10, v10
	v_and_b32_e32 v5, 0xffff0000, v5
	v_fmac_f32_e32 v4, v5, v5
	v_lshlrev_b32_e32 v5, 16, v6
	v_and_b32_e32 v6, 0xffff0000, v6
	v_mul_f32_e32 v6, v6, v6
	v_fmac_f32_e32 v6, v5, v5
	v_lshlrev_b32_e32 v5, 16, v7
	v_fmac_f32_e32 v6, v5, v5
	v_and_b32_e32 v5, 0xffff0000, v7
	v_fmac_f32_e32 v6, v5, v5
	v_add_f32_e32 v5, v9, v6
	v_lshlrev_b32_e32 v6, 16, v0
	v_and_b32_e32 v0, 0xffff0000, v0
	v_mul_f32_e32 v0, v0, v0
	v_fmac_f32_e32 v0, v6, v6
	v_lshlrev_b32_e32 v6, 16, v1
	v_fmac_f32_e32 v0, v6, v6
	v_and_b32_e32 v1, 0xffff0000, v1
	v_fmac_f32_e32 v0, v1, v1
	v_lshlrev_b32_e32 v1, 16, v2
	v_and_b32_e32 v2, 0xffff0000, v2
	v_mul_f32_e32 v2, v2, v2
	v_add_f32_e32 v12, v28, v12
	v_fmac_f32_e32 v2, v1, v1
	v_lshlrev_b32_e32 v1, 16, v3
	v_add_f32_e32 v8, v12, v8
	v_fmac_f32_e32 v2, v1, v1
	v_and_b32_e32 v1, 0xffff0000, v3
	v_add_f32_e32 v4, v8, v4
	v_fmac_f32_e32 v2, v1, v1
	v_add_f32_e32 v0, v4, v0
	v_add_f32_e32 v1, v5, v2
	v_add_f32_e32 v0, v0, v1
	v_fmamk_f32 v6, v0, 0x3f800347, v217
	ds_bpermute_b32 v0, v22, v17
	ds_bpermute_b32 v2, v22, v20
	ds_bpermute_b32 v4, v22, v21
	ds_bpermute_b32 v7, v22, v6
	s_waitcnt lgkmcnt(3)
	v_max_f32_e32 v0, v0, v0
	s_waitcnt lgkmcnt(2)
	v_max_f32_e32 v2, v2, v2
	s_waitcnt lgkmcnt(1)
	v_max_f32_e32 v4, v4, v4
	s_waitcnt lgkmcnt(0)
	v_max_f32_e32 v7, v7, v7
	v_max_f32_e32 v0, v17, v0
	v_max_f32_e32 v2, v20, v2
	v_max_f32_e32 v4, v21, v4
	v_max_f32_e32 v6, v6, v7
	ds_bpermute_b32 v1, v23, v0
	ds_bpermute_b32 v3, v23, v2
	ds_bpermute_b32 v5, v23, v4
	ds_bpermute_b32 v7, v23, v6
	s_waitcnt lgkmcnt(3)
	v_max_f32_e32 v1, v1, v1
	s_waitcnt lgkmcnt(2)
	v_max_f32_e32 v3, v3, v3
	s_waitcnt lgkmcnt(1)
	v_max_f32_e32 v5, v5, v5
	s_waitcnt lgkmcnt(0)
	v_max_f32_e32 v7, v7, v7
	v_max_f32_e32 v0, v0, v1
	v_max_f32_e32 v2, v2, v3
	v_max_f32_e32 v4, v4, v5
	v_max_f32_e32 v6, v6, v7
	ds_bpermute_b32 v1, v24, v0
	ds_bpermute_b32 v3, v24, v2
	ds_bpermute_b32 v5, v24, v4
	ds_bpermute_b32 v7, v24, v6
	s_waitcnt lgkmcnt(3)
	v_max_f32_e32 v1, v1, v1
	s_waitcnt lgkmcnt(2)
	v_max_f32_e32 v3, v3, v3
	s_waitcnt lgkmcnt(1)
	v_max_f32_e32 v5, v5, v5
	s_waitcnt lgkmcnt(0)
	v_max_f32_e32 v7, v7, v7
	v_max_f32_e32 v0, v0, v1
	v_max_f32_e32 v2, v2, v3
	v_max_f32_e32 v4, v4, v5
	v_max_f32_e32 v6, v6, v7
	ds_bpermute_b32 v1, v25, v0
	ds_bpermute_b32 v3, v25, v2
	ds_bpermute_b32 v5, v25, v4
	ds_bpermute_b32 v7, v25, v6
	s_and_saveexec_b64 s[42:43], s[38:39]
	s_cbranch_execz .LBB0_313
	s_waitcnt lgkmcnt(0)
	v_max_f32_e32 v7, v7, v7
	v_max_f32_e32 v6, v6, v6
	v_max_f32_e32 v1, v1, v1
	v_max_f32_e32 v0, v0, v0
	v_max_f32_e32 v6, v6, v7
	v_max_f32_e32 v7, v0, v1
	v_max_f32_e32 v0, v3, v3
	v_max_f32_e32 v1, v2, v2
	v_max_f32_e32 v8, v1, v0
	v_max_f32_e32 v0, v5, v5
	v_max_f32_e32 v1, v4, v4
	s_ashr_i32 s6, s0, 2
	v_max_f32_e32 v4, v1, v0
	v_and_or_b32 v0, s6, -8, v27
	v_ashrrev_i32_e32 v1, 31, v0
	v_lshl_add_u64 v[2:3], v[0:1], 3, s[40:41]
	v_or_b32_e32 v0, 1, v0
	v_ashrrev_i32_e32 v1, 31, v0
	global_atomic_umax v[2:3], v7, off
	v_lshl_add_u64 v[0:1], v[0:1], 3, s[40:41]
	global_atomic_umax v[0:1], v8, off
	global_atomic_umax v[2:3], v4, off offset:4
	global_atomic_umax v[0:1], v6, off offset:4
	s_branch .LBB0_313
